# E17 + GLA gate phases (layers 0,3) rewritten by hand: all row loads in flight at once, silu as z*rcp(1+exp2(-z*log2e)) in f32 (as the attention epilogue gate) instead of the expf+IEEE-div expansions
# speedup vs baseline: 1.0310x; 1.0205x over previous
; DI float bflo(u32 p) { return __uint_as_float(p << 16); }
; DI float bfhi(u32 p) { return __uint_as_float(p & 0xffff0000u); }
; DI void gate_phase(u16* hb, const u16* proj, int ld, int zoff, const float* w, int G, float scale) {
;     ...
;   for (int row = blockIdx.x * 8 + wv; row < MROWS; row += gridDim.x * 8) {
;     u32x2* hp = reinterpret_cast<u32x2*>(hb + (size_t)row * DM);
;     const u32x2* zp = reinterpret_cast<const u32x2*>(proj + (size_t)row * ld + zoff);
;     float o[8][4], ss[8];
; #pragma unroll
;     for (int i = 0; i < 8; ++i) {
;       const u32x2 pk = __builtin_nontemporal_load(hp + i * 64 + lane);
;       o[i][0] = bflo(pk.x); o[i][1] = bfhi(pk.x); o[i][2] = bflo(pk.y); o[i][3] = bfhi(pk.y);
;       ss[i] = o[i][0] * o[i][0] + o[i][1] * o[i][1] + o[i][2] * o[i][2] + o[i][3] * o[i][3];
;     }
; #pragma unroll
;     for (int i = 0; i < 8; ++i) ss[i] = wave_sum(ss[i]);
.LBB0_313:
	v_mad_i64_i32 v[16:17], s[4:5], v4, s13, v[6:7]
	v_ashrrev_i32_e32 v5, 31, v4
	v_lshlrev_b64 v[0:1], 12, v[4:5]
	v_lshl_add_u64 v[14:15], v[10:11], 0, v[0:1]
	v_add_u32_e32 v4, s3, v4
	global_load_dwordx2 v[100:101], v[14:15], off nt
	global_load_dwordx2 v[102:103], v[14:15], off offset:512 nt
	global_load_dwordx2 v[104:105], v[14:15], off offset:1024 nt
	global_load_dwordx2 v[106:107], v[14:15], off offset:1536 nt
	global_load_dwordx2 v[108:109], v[14:15], off offset:2048 nt
	global_load_dwordx2 v[110:111], v[14:15], off offset:2560 nt
	global_load_dwordx2 v[112:113], v[14:15], off offset:3072 nt
	global_load_dwordx2 v[114:115], v[14:15], off offset:3584 nt
	global_load_dwordx4 v[132:135], v[8:9], off
	global_load_dwordx4 v[136:139], v[8:9], off offset:1024
	global_load_dwordx2 v[116:117], v[16:17], off nt
	global_load_dwordx2 v[118:119], v[16:17], off offset:512 nt
	global_load_dwordx2 v[120:121], v[16:17], off offset:1024 nt
	global_load_dwordx2 v[122:123], v[16:17], off offset:1536 nt
	global_load_dwordx2 v[124:125], v[16:17], off offset:2048 nt
	global_load_dwordx2 v[126:127], v[16:17], off offset:2560 nt
	global_load_dwordx2 v[128:129], v[16:17], off offset:3072 nt
	global_load_dwordx2 v[130:131], v[16:17], off offset:3584 nt
	s_waitcnt vmcnt(17)
	v_lshlrev_b32_e32 v140, 16, v100
	v_and_b32_e32 v141, 0xffff0000, v100
	v_lshlrev_b32_e32 v142, 16, v101
	v_and_b32_e32 v143, 0xffff0000, v101
	v_mul_f32_e32 v172, v140, v140
	v_fmac_f32_e32 v172, v141, v141
	v_fmac_f32_e32 v172, v142, v142
	v_fmac_f32_e32 v172, v143, v143
	s_waitcnt vmcnt(16)
	v_lshlrev_b32_e32 v144, 16, v102
	v_and_b32_e32 v145, 0xffff0000, v102
	v_lshlrev_b32_e32 v146, 16, v103
	v_and_b32_e32 v147, 0xffff0000, v103
	v_mul_f32_e32 v173, v144, v144
	v_fmac_f32_e32 v173, v145, v145
	v_fmac_f32_e32 v173, v146, v146
	v_fmac_f32_e32 v173, v147, v147
	s_waitcnt vmcnt(15)
	v_lshlrev_b32_e32 v148, 16, v104
	v_and_b32_e32 v149, 0xffff0000, v104
	v_lshlrev_b32_e32 v150, 16, v105
	v_and_b32_e32 v151, 0xffff0000, v105
	v_mul_f32_e32 v174, v148, v148
	v_fmac_f32_e32 v174, v149, v149
	v_fmac_f32_e32 v174, v150, v150
	v_fmac_f32_e32 v174, v151, v151
	s_waitcnt vmcnt(14)
	v_lshlrev_b32_e32 v152, 16, v106
	v_and_b32_e32 v153, 0xffff0000, v106
	v_lshlrev_b32_e32 v154, 16, v107
	v_and_b32_e32 v155, 0xffff0000, v107
	v_mul_f32_e32 v175, v152, v152
	v_fmac_f32_e32 v175, v153, v153
	v_fmac_f32_e32 v175, v154, v154
	v_fmac_f32_e32 v175, v155, v155
	s_waitcnt vmcnt(13)
	v_lshlrev_b32_e32 v156, 16, v108
	v_and_b32_e32 v157, 0xffff0000, v108
	v_lshlrev_b32_e32 v158, 16, v109
	v_and_b32_e32 v159, 0xffff0000, v109
	v_mul_f32_e32 v176, v156, v156
	v_fmac_f32_e32 v176, v157, v157
	v_fmac_f32_e32 v176, v158, v158
	v_fmac_f32_e32 v176, v159, v159
	s_waitcnt vmcnt(12)
	v_lshlrev_b32_e32 v160, 16, v110
	v_and_b32_e32 v161, 0xffff0000, v110
	v_lshlrev_b32_e32 v162, 16, v111
	v_and_b32_e32 v163, 0xffff0000, v111
	v_mul_f32_e32 v177, v160, v160
	v_fmac_f32_e32 v177, v161, v161
	v_fmac_f32_e32 v177, v162, v162
	v_fmac_f32_e32 v177, v163, v163
	s_waitcnt vmcnt(11)
	v_lshlrev_b32_e32 v164, 16, v112
	v_and_b32_e32 v165, 0xffff0000, v112
	v_lshlrev_b32_e32 v166, 16, v113
	v_and_b32_e32 v167, 0xffff0000, v113
	v_mul_f32_e32 v178, v164, v164
	v_fmac_f32_e32 v178, v165, v165
	v_fmac_f32_e32 v178, v166, v166
	v_fmac_f32_e32 v178, v167, v167
	s_waitcnt vmcnt(10)
	v_lshlrev_b32_e32 v168, 16, v114
	v_and_b32_e32 v169, 0xffff0000, v114
	v_lshlrev_b32_e32 v170, 16, v115
	v_and_b32_e32 v171, 0xffff0000, v115
	v_mul_f32_e32 v179, v168, v168
	v_fmac_f32_e32 v179, v169, v169
	v_fmac_f32_e32 v179, v170, v170
	v_fmac_f32_e32 v179, v171, v171
	ds_bpermute_b32 v180, v34, v172
	ds_bpermute_b32 v181, v34, v173
	ds_bpermute_b32 v182, v34, v174
	ds_bpermute_b32 v183, v34, v175
	ds_bpermute_b32 v184, v34, v176
	ds_bpermute_b32 v185, v34, v177
	ds_bpermute_b32 v186, v34, v178
	ds_bpermute_b32 v187, v34, v179
	s_waitcnt lgkmcnt(0)
	v_add_f32_e32 v172, v172, v180
	v_add_f32_e32 v173, v173, v181
	v_add_f32_e32 v174, v174, v182
	v_add_f32_e32 v175, v175, v183
	v_add_f32_e32 v176, v176, v184
	v_add_f32_e32 v177, v177, v185
	v_add_f32_e32 v178, v178, v186
	v_add_f32_e32 v179, v179, v187
	ds_bpermute_b32 v180, v35, v172
	ds_bpermute_b32 v181, v35, v173
	ds_bpermute_b32 v182, v35, v174
	ds_bpermute_b32 v183, v35, v175
	ds_bpermute_b32 v184, v35, v176
	ds_bpermute_b32 v185, v35, v177
	ds_bpermute_b32 v186, v35, v178
	ds_bpermute_b32 v187, v35, v179
	s_waitcnt lgkmcnt(0)
	v_add_f32_e32 v172, v172, v180
	v_add_f32_e32 v173, v173, v181
	v_add_f32_e32 v174, v174, v182
	v_add_f32_e32 v175, v175, v183
	v_add_f32_e32 v176, v176, v184
	v_add_f32_e32 v177, v177, v185
	v_add_f32_e32 v178, v178, v186
	v_add_f32_e32 v179, v179, v187
	ds_bpermute_b32 v180, v36, v172
	ds_bpermute_b32 v181, v36, v173
	ds_bpermute_b32 v182, v36, v174
	ds_bpermute_b32 v183, v36, v175
	ds_bpermute_b32 v184, v36, v176
	ds_bpermute_b32 v185, v36, v177
	ds_bpermute_b32 v186, v36, v178
	ds_bpermute_b32 v187, v36, v179
	s_waitcnt lgkmcnt(0)
	v_add_f32_e32 v172, v172, v180
	v_add_f32_e32 v173, v173, v181
	v_add_f32_e32 v174, v174, v182
	v_add_f32_e32 v175, v175, v183
	v_add_f32_e32 v176, v176, v184
	v_add_f32_e32 v177, v177, v185
	v_add_f32_e32 v178, v178, v186
	v_add_f32_e32 v179, v179, v187
	ds_bpermute_b32 v180, v37, v172
	ds_bpermute_b32 v181, v37, v173
	ds_bpermute_b32 v182, v37, v174
	ds_bpermute_b32 v183, v37, v175
	ds_bpermute_b32 v184, v37, v176
	ds_bpermute_b32 v185, v37, v177
	ds_bpermute_b32 v186, v37, v178
	ds_bpermute_b32 v187, v37, v179
	s_waitcnt lgkmcnt(0)
; DI u32 pack2(float a, float b) { f32v2 v = {a, b}; return __builtin_bit_cast(u32, __builtin_convertvector(v, bf16v2)); }
; DI float bflo(u32 p) { return __uint_as_float(p << 16); }
; DI float bfhi(u32 p) { return __uint_as_float(p & 0xffff0000u); }
; DI void gate_phase(u16* hb, const u16* proj, int ld, int zoff, const float* w, int G, float scale) {
;     ...
;     for (int i = 0; i < 8; ++i) ss[i] = wave_sum(ss[i]);
;     if (G == 512) {
; #pragma unroll
;       for (int i = 0; i < 8; i += 2) { const float t = ss[i] + ss[i + 1]; ss[i] = t; ss[i + 1] = t; }
;     } else if (G == 2048) {
;       float t = 0.f;
; #pragma unroll
;       for (int i = 0; i < 8; ++i) t += ss[i];
; #pragma unroll
;       for (int i = 0; i < 8; ++i) ss[i] = t;
;     }
;     const float invG = 1.f / (float)G;
; #pragma unroll
;     for (int i = 0; i < 8; ++i) {
;       const float r = rsqrtf(ss[i] * invG + 1e-6f) * scale;
;       const int col = i * 256 + lane * 4;
;       const float4 ww = *reinterpret_cast<const float4*>(w + (col & (G - 1)));
;       const u32x2 zk = __builtin_nontemporal_load(zp + i * 64 + lane);
;       const float z0 = bflo(zk.x), z1 = bfhi(zk.x), z2 = bflo(zk.y), z3 = bfhi(zk.y);
;       const float g0 = o[i][0] * r * ww.x * (z0 / (1.f + expf(-z0)));
;       const float g1 = o[i][1] * r * ww.y * (z1 / (1.f + expf(-z1)));
;       const float g2 = o[i][2] * r * ww.z * (z2 / (1.f + expf(-z2)));
;       const float g3 = o[i][3] * r * ww.w * (z3 / (1.f + expf(-z3)));
;       u32x2 ov = {pack2(g0, g1), pack2(g2, g3)};
;       hp[i * 64 + lane] = ov;
	v_add_f32_e32 v172, v172, v180
	v_add_f32_e32 v173, v173, v181
	v_add_f32_e32 v174, v174, v182
	v_add_f32_e32 v175, v175, v183
	v_add_f32_e32 v176, v176, v184
	v_add_f32_e32 v177, v177, v185
	v_add_f32_e32 v178, v178, v186
	v_add_f32_e32 v179, v179, v187
	ds_bpermute_b32 v180, v38, v172
	ds_bpermute_b32 v181, v38, v173
	ds_bpermute_b32 v182, v38, v174
	ds_bpermute_b32 v183, v38, v175
	ds_bpermute_b32 v184, v38, v176
	ds_bpermute_b32 v185, v38, v177
	ds_bpermute_b32 v186, v38, v178
	ds_bpermute_b32 v187, v38, v179
	s_waitcnt lgkmcnt(0)
	v_add_f32_e32 v172, v172, v180
	v_add_f32_e32 v173, v173, v181
	v_add_f32_e32 v174, v174, v182
	v_add_f32_e32 v175, v175, v183
	v_add_f32_e32 v176, v176, v184
	v_add_f32_e32 v177, v177, v185
	v_add_f32_e32 v178, v178, v186
	v_add_f32_e32 v179, v179, v187
	ds_bpermute_b32 v180, v39, v172
	ds_bpermute_b32 v181, v39, v173
	ds_bpermute_b32 v182, v39, v174
	ds_bpermute_b32 v183, v39, v175
	ds_bpermute_b32 v184, v39, v176
	ds_bpermute_b32 v185, v39, v177
	ds_bpermute_b32 v186, v39, v178
	ds_bpermute_b32 v187, v39, v179
	s_waitcnt lgkmcnt(0)
	v_add_f32_e32 v172, v172, v180
	v_add_f32_e32 v173, v173, v181
	v_add_f32_e32 v174, v174, v182
	v_add_f32_e32 v175, v175, v183
	v_add_f32_e32 v176, v176, v184
	v_add_f32_e32 v177, v177, v185
	v_add_f32_e32 v178, v178, v186
	v_add_f32_e32 v179, v179, v187
	v_add_f32_e32 v180, v172, v173
	v_add_f32_e32 v182, v174, v175
	v_add_f32_e32 v184, v176, v177
	v_add_f32_e32 v186, v178, v179
	v_fma_f32 v180, v180, s12, v12
	v_fma_f32 v182, v182, s12, v12
	v_fma_f32 v184, v184, s12, v12
	v_fma_f32 v186, v186, s12, v12
	v_rsq_f32_e32 v180, v180
	v_rsq_f32_e32 v182, v182
	v_rsq_f32_e32 v184, v184
	v_rsq_f32_e32 v186, v186
	s_waitcnt vmcnt(0)
	v_lshlrev_b32_e32 v188, 16, v116
	v_and_b32_e32 v189, 0xffff0000, v116
	v_lshlrev_b32_e32 v190, 16, v117
	v_and_b32_e32 v191, 0xffff0000, v117
	v_mul_f32_e32 v192, 0xbfb8aa3b, v188
	v_mul_f32_e32 v193, 0xbfb8aa3b, v189
	v_mul_f32_e32 v194, 0xbfb8aa3b, v190
	v_mul_f32_e32 v195, 0xbfb8aa3b, v191
	v_exp_f32_e32 v192, v192
	v_exp_f32_e32 v193, v193
	v_exp_f32_e32 v194, v194
	v_exp_f32_e32 v195, v195
	v_mul_f32_e32 v140, v140, v180
	v_mul_f32_e32 v141, v141, v180
	v_mul_f32_e32 v142, v142, v180
	v_mul_f32_e32 v143, v143, v180
	v_add_f32_e32 v192, 1.0, v192
	v_add_f32_e32 v193, 1.0, v193
	v_add_f32_e32 v194, 1.0, v194
	v_add_f32_e32 v195, 1.0, v195
	v_rcp_f32_e32 v192, v192
	v_rcp_f32_e32 v193, v193
	v_rcp_f32_e32 v194, v194
	v_rcp_f32_e32 v195, v195
	v_mul_f32_e32 v140, v140, v132
	v_mul_f32_e32 v141, v141, v133
	v_mul_f32_e32 v142, v142, v134
	v_mul_f32_e32 v143, v143, v135
	v_mul_f32_e32 v192, v188, v192
	v_mul_f32_e32 v193, v189, v193
	v_mul_f32_e32 v194, v190, v194
	v_mul_f32_e32 v195, v191, v195
	v_mul_f32_e32 v140, v140, v192
	v_mul_f32_e32 v141, v141, v193
	v_mul_f32_e32 v142, v142, v194
	v_mul_f32_e32 v143, v143, v195
	v_cvt_pk_bf16_f32 v212, v140, v141
	v_cvt_pk_bf16_f32 v213, v142, v143
	global_store_dwordx2 v[14:15], v[212:213], off
	v_lshlrev_b32_e32 v188, 16, v118
	v_and_b32_e32 v189, 0xffff0000, v118
	v_lshlrev_b32_e32 v190, 16, v119
	v_and_b32_e32 v191, 0xffff0000, v119
	v_mul_f32_e32 v192, 0xbfb8aa3b, v188
	v_mul_f32_e32 v193, 0xbfb8aa3b, v189
	v_mul_f32_e32 v194, 0xbfb8aa3b, v190
	v_mul_f32_e32 v195, 0xbfb8aa3b, v191
	v_exp_f32_e32 v192, v192
	v_exp_f32_e32 v193, v193
	v_exp_f32_e32 v194, v194
	v_exp_f32_e32 v195, v195
	v_mul_f32_e32 v144, v144, v180
	v_mul_f32_e32 v145, v145, v180
	v_mul_f32_e32 v146, v146, v180
	v_mul_f32_e32 v147, v147, v180
	v_add_f32_e32 v192, 1.0, v192
	v_add_f32_e32 v193, 1.0, v193
	v_add_f32_e32 v194, 1.0, v194
	v_add_f32_e32 v195, 1.0, v195
	v_rcp_f32_e32 v192, v192
	v_rcp_f32_e32 v193, v193
	v_rcp_f32_e32 v194, v194
	v_rcp_f32_e32 v195, v195
	v_mul_f32_e32 v144, v144, v136
	v_mul_f32_e32 v145, v145, v137
	v_mul_f32_e32 v146, v146, v138
	v_mul_f32_e32 v147, v147, v139
	v_mul_f32_e32 v192, v188, v192
	v_mul_f32_e32 v193, v189, v193
	v_mul_f32_e32 v194, v190, v194
	v_mul_f32_e32 v195, v191, v195
	v_mul_f32_e32 v144, v144, v192
	v_mul_f32_e32 v145, v145, v193
	v_mul_f32_e32 v146, v146, v194
	v_mul_f32_e32 v147, v147, v195
	v_cvt_pk_bf16_f32 v214, v144, v145
	v_cvt_pk_bf16_f32 v215, v146, v147
	global_store_dwordx2 v[14:15], v[214:215], off offset:512
	v_lshlrev_b32_e32 v188, 16, v120
	v_and_b32_e32 v189, 0xffff0000, v120
	v_lshlrev_b32_e32 v190, 16, v121
	v_and_b32_e32 v191, 0xffff0000, v121
	v_mul_f32_e32 v192, 0xbfb8aa3b, v188
	v_mul_f32_e32 v193, 0xbfb8aa3b, v189
	v_mul_f32_e32 v194, 0xbfb8aa3b, v190
	v_mul_f32_e32 v195, 0xbfb8aa3b, v191
	v_exp_f32_e32 v192, v192
	v_exp_f32_e32 v193, v193
	v_exp_f32_e32 v194, v194
	v_exp_f32_e32 v195, v195
	v_mul_f32_e32 v148, v148, v182
	v_mul_f32_e32 v149, v149, v182
	v_mul_f32_e32 v150, v150, v182
	v_mul_f32_e32 v151, v151, v182
	v_add_f32_e32 v192, 1.0, v192
	v_add_f32_e32 v193, 1.0, v193
	v_add_f32_e32 v194, 1.0, v194
	v_add_f32_e32 v195, 1.0, v195
	v_rcp_f32_e32 v192, v192
	v_rcp_f32_e32 v193, v193
	v_rcp_f32_e32 v194, v194
	v_rcp_f32_e32 v195, v195
	v_mul_f32_e32 v148, v148, v132
	v_mul_f32_e32 v149, v149, v133
	v_mul_f32_e32 v150, v150, v134
	v_mul_f32_e32 v151, v151, v135
	v_mul_f32_e32 v192, v188, v192
	v_mul_f32_e32 v193, v189, v193
	v_mul_f32_e32 v194, v190, v194
	v_mul_f32_e32 v195, v191, v195
	v_mul_f32_e32 v148, v148, v192
	v_mul_f32_e32 v149, v149, v193
	v_mul_f32_e32 v150, v150, v194
	v_mul_f32_e32 v151, v151, v195
	v_cvt_pk_bf16_f32 v216, v148, v149
	v_cvt_pk_bf16_f32 v217, v150, v151
	global_store_dwordx2 v[14:15], v[216:217], off offset:1024
	v_lshlrev_b32_e32 v188, 16, v122
	v_and_b32_e32 v189, 0xffff0000, v122
	v_lshlrev_b32_e32 v190, 16, v123
; DI u32 pack2(float a, float b) { f32v2 v = {a, b}; return __builtin_bit_cast(u32, __builtin_convertvector(v, bf16v2)); }
; DI float bflo(u32 p) { return __uint_as_float(p << 16); }
; DI float bfhi(u32 p) { return __uint_as_float(p & 0xffff0000u); }
; DI void gate_phase(u16* hb, const u16* proj, int ld, int zoff, const float* w, int G, float scale) {
;     ...
; #pragma unroll
;     for (int i = 0; i < 8; ++i) {
;       const float r = rsqrtf(ss[i] * invG + 1e-6f) * scale;
;       const int col = i * 256 + lane * 4;
;       const float4 ww = *reinterpret_cast<const float4*>(w + (col & (G - 1)));
;       const u32x2 zk = __builtin_nontemporal_load(zp + i * 64 + lane);
;       const float z0 = bflo(zk.x), z1 = bfhi(zk.x), z2 = bflo(zk.y), z3 = bfhi(zk.y);
;       const float g0 = o[i][0] * r * ww.x * (z0 / (1.f + expf(-z0)));
;       const float g1 = o[i][1] * r * ww.y * (z1 / (1.f + expf(-z1)));
;       const float g2 = o[i][2] * r * ww.z * (z2 / (1.f + expf(-z2)));
;       const float g3 = o[i][3] * r * ww.w * (z3 / (1.f + expf(-z3)));
;       u32x2 ov = {pack2(g0, g1), pack2(g2, g3)};
;       hp[i * 64 + lane] = ov;
;     }
	v_and_b32_e32 v191, 0xffff0000, v123
	v_mul_f32_e32 v192, 0xbfb8aa3b, v188
	v_mul_f32_e32 v193, 0xbfb8aa3b, v189
	v_mul_f32_e32 v194, 0xbfb8aa3b, v190
	v_mul_f32_e32 v195, 0xbfb8aa3b, v191
	v_exp_f32_e32 v192, v192
	v_exp_f32_e32 v193, v193
	v_exp_f32_e32 v194, v194
	v_exp_f32_e32 v195, v195
	v_mul_f32_e32 v152, v152, v182
	v_mul_f32_e32 v153, v153, v182
	v_mul_f32_e32 v154, v154, v182
	v_mul_f32_e32 v155, v155, v182
	v_add_f32_e32 v192, 1.0, v192
	v_add_f32_e32 v193, 1.0, v193
	v_add_f32_e32 v194, 1.0, v194
	v_add_f32_e32 v195, 1.0, v195
	v_rcp_f32_e32 v192, v192
	v_rcp_f32_e32 v193, v193
	v_rcp_f32_e32 v194, v194
	v_rcp_f32_e32 v195, v195
	v_mul_f32_e32 v152, v152, v136
	v_mul_f32_e32 v153, v153, v137
	v_mul_f32_e32 v154, v154, v138
	v_mul_f32_e32 v155, v155, v139
	v_mul_f32_e32 v192, v188, v192
	v_mul_f32_e32 v193, v189, v193
	v_mul_f32_e32 v194, v190, v194
	v_mul_f32_e32 v195, v191, v195
	v_mul_f32_e32 v152, v152, v192
	v_mul_f32_e32 v153, v153, v193
	v_mul_f32_e32 v154, v154, v194
	v_mul_f32_e32 v155, v155, v195
	v_cvt_pk_bf16_f32 v218, v152, v153
	v_cvt_pk_bf16_f32 v219, v154, v155
	global_store_dwordx2 v[14:15], v[218:219], off offset:1536
	v_lshlrev_b32_e32 v188, 16, v124
	v_and_b32_e32 v189, 0xffff0000, v124
	v_lshlrev_b32_e32 v190, 16, v125
	v_and_b32_e32 v191, 0xffff0000, v125
	v_mul_f32_e32 v192, 0xbfb8aa3b, v188
	v_mul_f32_e32 v193, 0xbfb8aa3b, v189
	v_mul_f32_e32 v194, 0xbfb8aa3b, v190
	v_mul_f32_e32 v195, 0xbfb8aa3b, v191
	v_exp_f32_e32 v192, v192
	v_exp_f32_e32 v193, v193
	v_exp_f32_e32 v194, v194
	v_exp_f32_e32 v195, v195
	v_mul_f32_e32 v156, v156, v184
	v_mul_f32_e32 v157, v157, v184
	v_mul_f32_e32 v158, v158, v184
	v_mul_f32_e32 v159, v159, v184
	v_add_f32_e32 v192, 1.0, v192
	v_add_f32_e32 v193, 1.0, v193
	v_add_f32_e32 v194, 1.0, v194
	v_add_f32_e32 v195, 1.0, v195
	v_rcp_f32_e32 v192, v192
	v_rcp_f32_e32 v193, v193
	v_rcp_f32_e32 v194, v194
	v_rcp_f32_e32 v195, v195
	v_mul_f32_e32 v156, v156, v132
	v_mul_f32_e32 v157, v157, v133
	v_mul_f32_e32 v158, v158, v134
	v_mul_f32_e32 v159, v159, v135
	v_mul_f32_e32 v192, v188, v192
	v_mul_f32_e32 v193, v189, v193
	v_mul_f32_e32 v194, v190, v194
	v_mul_f32_e32 v195, v191, v195
	v_mul_f32_e32 v156, v156, v192
	v_mul_f32_e32 v157, v157, v193
	v_mul_f32_e32 v158, v158, v194
	v_mul_f32_e32 v159, v159, v195
	v_cvt_pk_bf16_f32 v220, v156, v157
	v_cvt_pk_bf16_f32 v221, v158, v159
	global_store_dwordx2 v[14:15], v[220:221], off offset:2048
	v_lshlrev_b32_e32 v188, 16, v126
	v_and_b32_e32 v189, 0xffff0000, v126
	v_lshlrev_b32_e32 v190, 16, v127
	v_and_b32_e32 v191, 0xffff0000, v127
	v_mul_f32_e32 v192, 0xbfb8aa3b, v188
	v_mul_f32_e32 v193, 0xbfb8aa3b, v189
	v_mul_f32_e32 v194, 0xbfb8aa3b, v190
	v_mul_f32_e32 v195, 0xbfb8aa3b, v191
	v_exp_f32_e32 v192, v192
	v_exp_f32_e32 v193, v193
	v_exp_f32_e32 v194, v194
	v_exp_f32_e32 v195, v195
	v_mul_f32_e32 v160, v160, v184
	v_mul_f32_e32 v161, v161, v184
	v_mul_f32_e32 v162, v162, v184
	v_mul_f32_e32 v163, v163, v184
	v_add_f32_e32 v192, 1.0, v192
	v_add_f32_e32 v193, 1.0, v193
	v_add_f32_e32 v194, 1.0, v194
	v_add_f32_e32 v195, 1.0, v195
	v_rcp_f32_e32 v192, v192
	v_rcp_f32_e32 v193, v193
	v_rcp_f32_e32 v194, v194
	v_rcp_f32_e32 v195, v195
	v_mul_f32_e32 v160, v160, v136
	v_mul_f32_e32 v161, v161, v137
	v_mul_f32_e32 v162, v162, v138
	v_mul_f32_e32 v163, v163, v139
	v_mul_f32_e32 v192, v188, v192
	v_mul_f32_e32 v193, v189, v193
	v_mul_f32_e32 v194, v190, v194
	v_mul_f32_e32 v195, v191, v195
	v_mul_f32_e32 v160, v160, v192
	v_mul_f32_e32 v161, v161, v193
	v_mul_f32_e32 v162, v162, v194
	v_mul_f32_e32 v163, v163, v195
	v_cvt_pk_bf16_f32 v222, v160, v161
	v_cvt_pk_bf16_f32 v223, v162, v163
	global_store_dwordx2 v[14:15], v[222:223], off offset:2560
	v_lshlrev_b32_e32 v188, 16, v128
	v_and_b32_e32 v189, 0xffff0000, v128
	v_lshlrev_b32_e32 v190, 16, v129
	v_and_b32_e32 v191, 0xffff0000, v129
	v_mul_f32_e32 v192, 0xbfb8aa3b, v188
	v_mul_f32_e32 v193, 0xbfb8aa3b, v189
	v_mul_f32_e32 v194, 0xbfb8aa3b, v190
	v_mul_f32_e32 v195, 0xbfb8aa3b, v191
	v_exp_f32_e32 v192, v192
	v_exp_f32_e32 v193, v193
	v_exp_f32_e32 v194, v194
	v_exp_f32_e32 v195, v195
	v_mul_f32_e32 v164, v164, v186
	v_mul_f32_e32 v165, v165, v186
	v_mul_f32_e32 v166, v166, v186
	v_mul_f32_e32 v167, v167, v186
	v_add_f32_e32 v192, 1.0, v192
	v_add_f32_e32 v193, 1.0, v193
	v_add_f32_e32 v194, 1.0, v194
	v_add_f32_e32 v195, 1.0, v195
	v_rcp_f32_e32 v192, v192
	v_rcp_f32_e32 v193, v193
	v_rcp_f32_e32 v194, v194
	v_rcp_f32_e32 v195, v195
	v_mul_f32_e32 v164, v164, v132
	v_mul_f32_e32 v165, v165, v133
	v_mul_f32_e32 v166, v166, v134
	v_mul_f32_e32 v167, v167, v135
	v_mul_f32_e32 v192, v188, v192
	v_mul_f32_e32 v193, v189, v193
	v_mul_f32_e32 v194, v190, v194
	v_mul_f32_e32 v195, v191, v195
	v_mul_f32_e32 v164, v164, v192
	v_mul_f32_e32 v165, v165, v193
	v_mul_f32_e32 v166, v166, v194
	v_mul_f32_e32 v167, v167, v195
	v_cvt_pk_bf16_f32 v224, v164, v165
	v_cvt_pk_bf16_f32 v225, v166, v167
	global_store_dwordx2 v[14:15], v[224:225], off offset:3072
	v_lshlrev_b32_e32 v188, 16, v130
	v_and_b32_e32 v189, 0xffff0000, v130
	v_lshlrev_b32_e32 v190, 16, v131
	v_and_b32_e32 v191, 0xffff0000, v131
	v_mul_f32_e32 v192, 0xbfb8aa3b, v188
	v_mul_f32_e32 v193, 0xbfb8aa3b, v189
	v_mul_f32_e32 v194, 0xbfb8aa3b, v190
	v_mul_f32_e32 v195, 0xbfb8aa3b, v191
	v_exp_f32_e32 v192, v192
	v_exp_f32_e32 v193, v193
	v_exp_f32_e32 v194, v194
	v_exp_f32_e32 v195, v195
	v_mul_f32_e32 v168, v168, v186
	v_mul_f32_e32 v169, v169, v186
	v_mul_f32_e32 v170, v170, v186
	v_mul_f32_e32 v171, v171, v186
	v_add_f32_e32 v192, 1.0, v192
	v_add_f32_e32 v193, 1.0, v193
	v_add_f32_e32 v194, 1.0, v194
	v_add_f32_e32 v195, 1.0, v195
	v_rcp_f32_e32 v192, v192
	v_rcp_f32_e32 v193, v193
	v_rcp_f32_e32 v194, v194
	v_rcp_f32_e32 v195, v195
	v_mul_f32_e32 v168, v168, v136
	v_mul_f32_e32 v169, v169, v137
	v_mul_f32_e32 v170, v170, v138
	v_mul_f32_e32 v171, v171, v139
	v_mul_f32_e32 v192, v188, v192
	v_mul_f32_e32 v193, v189, v193
	v_mul_f32_e32 v194, v190, v194
	v_mul_f32_e32 v195, v191, v195
	v_mul_f32_e32 v168, v168, v192
	v_mul_f32_e32 v169, v169, v193
	v_mul_f32_e32 v170, v170, v194
	v_mul_f32_e32 v171, v171, v195
	v_cvt_pk_bf16_f32 v226, v168, v169
	v_cvt_pk_bf16_f32 v227, v170, v171
	global_store_dwordx2 v[14:15], v[226:227], off offset:3584
	v_cmp_lt_i32_e32 vcc, s18, v4
	s_nop 1
	s_or_b64 s[10:11], vcc, s[10:11]
	s_andn2_b64 exec, exec, s[10:11]
	s_cbranch_execnz .LBB0_313

; DI float bflo(u32 p) { return __uint_as_float(p << 16); }
; DI float bfhi(u32 p) { return __uint_as_float(p & 0xffff0000u); }
; DI void gate_phase(u16* hb, const u16* proj, int ld, int zoff, const float* w, int G, float scale) {
;     ...
;   for (int row = blockIdx.x * 8 + wv; row < MROWS; row += gridDim.x * 8) {
;     u32x2* hp = reinterpret_cast<u32x2*>(hb + (size_t)row * DM);
;     const u32x2* zp = reinterpret_cast<const u32x2*>(proj + (size_t)row * ld + zoff);
;     float o[8][4], ss[8];
; #pragma unroll
;     for (int i = 0; i < 8; ++i) {
;       const u32x2 pk = __builtin_nontemporal_load(hp + i * 64 + lane);
;       o[i][0] = bflo(pk.x); o[i][1] = bfhi(pk.x); o[i][2] = bflo(pk.y); o[i][3] = bfhi(pk.y);
;       ss[i] = o[i][0] * o[i][0] + o[i][1] * o[i][1] + o[i][2] * o[i][2] + o[i][3] * o[i][3];
;     }
; #pragma unroll
;     for (int i = 0; i < 8; ++i) ss[i] = wave_sum(ss[i]);
.LBB0_1483:
	v_mad_i64_i32 v[16:17], s[6:7], v4, s5, v[6:7]
	v_ashrrev_i32_e32 v5, 31, v4
	v_lshlrev_b64 v[0:1], 12, v[4:5]
	v_lshl_add_u64 v[14:15], v[10:11], 0, v[0:1]
	v_add_u32_e32 v4, s4, v4
	global_load_dwordx2 v[100:101], v[14:15], off nt
	global_load_dwordx2 v[102:103], v[14:15], off offset:512 nt
	global_load_dwordx2 v[104:105], v[14:15], off offset:1024 nt
	global_load_dwordx2 v[106:107], v[14:15], off offset:1536 nt
	global_load_dwordx2 v[108:109], v[14:15], off offset:2048 nt
	global_load_dwordx2 v[110:111], v[14:15], off offset:2560 nt
	global_load_dwordx2 v[112:113], v[14:15], off offset:3072 nt
	global_load_dwordx2 v[114:115], v[14:15], off offset:3584 nt
	global_load_dwordx4 v[132:135], v[8:9], off offset:2048
	global_load_dwordx4 v[136:139], v[8:9], off offset:3072
	global_load_dwordx2 v[116:117], v[16:17], off nt
	global_load_dwordx2 v[118:119], v[16:17], off offset:512 nt
	global_load_dwordx2 v[120:121], v[16:17], off offset:1024 nt
	global_load_dwordx2 v[122:123], v[16:17], off offset:1536 nt
	global_load_dwordx2 v[124:125], v[16:17], off offset:2048 nt
	global_load_dwordx2 v[126:127], v[16:17], off offset:2560 nt
	global_load_dwordx2 v[128:129], v[16:17], off offset:3072 nt
	global_load_dwordx2 v[130:131], v[16:17], off offset:3584 nt
	s_waitcnt vmcnt(17)
	v_lshlrev_b32_e32 v140, 16, v100
	v_and_b32_e32 v141, 0xffff0000, v100
	v_lshlrev_b32_e32 v142, 16, v101
	v_and_b32_e32 v143, 0xffff0000, v101
	v_mul_f32_e32 v172, v140, v140
	v_fmac_f32_e32 v172, v141, v141
	v_fmac_f32_e32 v172, v142, v142
	v_fmac_f32_e32 v172, v143, v143
	s_waitcnt vmcnt(16)
	v_lshlrev_b32_e32 v144, 16, v102
	v_and_b32_e32 v145, 0xffff0000, v102
	v_lshlrev_b32_e32 v146, 16, v103
	v_and_b32_e32 v147, 0xffff0000, v103
	v_mul_f32_e32 v173, v144, v144
	v_fmac_f32_e32 v173, v145, v145
	v_fmac_f32_e32 v173, v146, v146
	v_fmac_f32_e32 v173, v147, v147
	s_waitcnt vmcnt(15)
	v_lshlrev_b32_e32 v148, 16, v104
	v_and_b32_e32 v149, 0xffff0000, v104
	v_lshlrev_b32_e32 v150, 16, v105
	v_and_b32_e32 v151, 0xffff0000, v105
	v_mul_f32_e32 v174, v148, v148
	v_fmac_f32_e32 v174, v149, v149
	v_fmac_f32_e32 v174, v150, v150
	v_fmac_f32_e32 v174, v151, v151
	s_waitcnt vmcnt(14)
	v_lshlrev_b32_e32 v152, 16, v106
	v_and_b32_e32 v153, 0xffff0000, v106
	v_lshlrev_b32_e32 v154, 16, v107
	v_and_b32_e32 v155, 0xffff0000, v107
	v_mul_f32_e32 v175, v152, v152
	v_fmac_f32_e32 v175, v153, v153
	v_fmac_f32_e32 v175, v154, v154
	v_fmac_f32_e32 v175, v155, v155
	s_waitcnt vmcnt(13)
	v_lshlrev_b32_e32 v156, 16, v108
	v_and_b32_e32 v157, 0xffff0000, v108
	v_lshlrev_b32_e32 v158, 16, v109
	v_and_b32_e32 v159, 0xffff0000, v109
	v_mul_f32_e32 v176, v156, v156
	v_fmac_f32_e32 v176, v157, v157
	v_fmac_f32_e32 v176, v158, v158
	v_fmac_f32_e32 v176, v159, v159
	s_waitcnt vmcnt(12)
	v_lshlrev_b32_e32 v160, 16, v110
	v_and_b32_e32 v161, 0xffff0000, v110
	v_lshlrev_b32_e32 v162, 16, v111
	v_and_b32_e32 v163, 0xffff0000, v111
	v_mul_f32_e32 v177, v160, v160
	v_fmac_f32_e32 v177, v161, v161
	v_fmac_f32_e32 v177, v162, v162
	v_fmac_f32_e32 v177, v163, v163
	s_waitcnt vmcnt(11)
	v_lshlrev_b32_e32 v164, 16, v112
	v_and_b32_e32 v165, 0xffff0000, v112
	v_lshlrev_b32_e32 v166, 16, v113
	v_and_b32_e32 v167, 0xffff0000, v113
	v_mul_f32_e32 v178, v164, v164
	v_fmac_f32_e32 v178, v165, v165
	v_fmac_f32_e32 v178, v166, v166
	v_fmac_f32_e32 v178, v167, v167
	s_waitcnt vmcnt(10)
	v_lshlrev_b32_e32 v168, 16, v114
	v_and_b32_e32 v169, 0xffff0000, v114
	v_lshlrev_b32_e32 v170, 16, v115
	v_and_b32_e32 v171, 0xffff0000, v115
	v_mul_f32_e32 v179, v168, v168
	v_fmac_f32_e32 v179, v169, v169
	v_fmac_f32_e32 v179, v170, v170
	v_fmac_f32_e32 v179, v171, v171
	ds_bpermute_b32 v180, v34, v172
	ds_bpermute_b32 v181, v34, v173
	ds_bpermute_b32 v182, v34, v174
	ds_bpermute_b32 v183, v34, v175
	ds_bpermute_b32 v184, v34, v176
	ds_bpermute_b32 v185, v34, v177
	ds_bpermute_b32 v186, v34, v178
	ds_bpermute_b32 v187, v34, v179
	s_waitcnt lgkmcnt(0)
	v_add_f32_e32 v172, v172, v180
	v_add_f32_e32 v173, v173, v181
	v_add_f32_e32 v174, v174, v182
	v_add_f32_e32 v175, v175, v183
	v_add_f32_e32 v176, v176, v184
	v_add_f32_e32 v177, v177, v185
	v_add_f32_e32 v178, v178, v186
	v_add_f32_e32 v179, v179, v187
	ds_bpermute_b32 v180, v35, v172
	ds_bpermute_b32 v181, v35, v173
	ds_bpermute_b32 v182, v35, v174
	ds_bpermute_b32 v183, v35, v175
	ds_bpermute_b32 v184, v35, v176
	ds_bpermute_b32 v185, v35, v177
	ds_bpermute_b32 v186, v35, v178
	ds_bpermute_b32 v187, v35, v179
	s_waitcnt lgkmcnt(0)
	v_add_f32_e32 v172, v172, v180
	v_add_f32_e32 v173, v173, v181
	v_add_f32_e32 v174, v174, v182
	v_add_f32_e32 v175, v175, v183
	v_add_f32_e32 v176, v176, v184
	v_add_f32_e32 v177, v177, v185
	v_add_f32_e32 v178, v178, v186
	v_add_f32_e32 v179, v179, v187
	ds_bpermute_b32 v180, v36, v172
	ds_bpermute_b32 v181, v36, v173
	ds_bpermute_b32 v182, v36, v174
	ds_bpermute_b32 v183, v36, v175
	ds_bpermute_b32 v184, v36, v176
	ds_bpermute_b32 v185, v36, v177
	ds_bpermute_b32 v186, v36, v178
	ds_bpermute_b32 v187, v36, v179
	s_waitcnt lgkmcnt(0)
	v_add_f32_e32 v172, v172, v180
	v_add_f32_e32 v173, v173, v181
	v_add_f32_e32 v174, v174, v182
	v_add_f32_e32 v175, v175, v183
	v_add_f32_e32 v176, v176, v184
	v_add_f32_e32 v177, v177, v185
	v_add_f32_e32 v178, v178, v186
	v_add_f32_e32 v179, v179, v187
	ds_bpermute_b32 v180, v37, v172
	ds_bpermute_b32 v181, v37, v173
	ds_bpermute_b32 v182, v37, v174
	ds_bpermute_b32 v183, v37, v175
	ds_bpermute_b32 v184, v37, v176
	ds_bpermute_b32 v185, v37, v177
	ds_bpermute_b32 v186, v37, v178
	ds_bpermute_b32 v187, v37, v179
	s_waitcnt lgkmcnt(0)
; DI u32 pack2(float a, float b) { f32v2 v = {a, b}; return __builtin_bit_cast(u32, __builtin_convertvector(v, bf16v2)); }
; DI float bflo(u32 p) { return __uint_as_float(p << 16); }
; DI float bfhi(u32 p) { return __uint_as_float(p & 0xffff0000u); }
; DI void gate_phase(u16* hb, const u16* proj, int ld, int zoff, const float* w, int G, float scale) {
;     ...
;     for (int i = 0; i < 8; ++i) ss[i] = wave_sum(ss[i]);
;     if (G == 512) {
; #pragma unroll
;       for (int i = 0; i < 8; i += 2) { const float t = ss[i] + ss[i + 1]; ss[i] = t; ss[i + 1] = t; }
;     } else if (G == 2048) {
;       float t = 0.f;
; #pragma unroll
;       for (int i = 0; i < 8; ++i) t += ss[i];
; #pragma unroll
;       for (int i = 0; i < 8; ++i) ss[i] = t;
;     }
;     const float invG = 1.f / (float)G;
; #pragma unroll
;     for (int i = 0; i < 8; ++i) {
;       const float r = rsqrtf(ss[i] * invG + 1e-6f) * scale;
;       const int col = i * 256 + lane * 4;
;       const float4 ww = *reinterpret_cast<const float4*>(w + (col & (G - 1)));
;       const u32x2 zk = __builtin_nontemporal_load(zp + i * 64 + lane);
;       const float z0 = bflo(zk.x), z1 = bfhi(zk.x), z2 = bflo(zk.y), z3 = bfhi(zk.y);
;       const float g0 = o[i][0] * r * ww.x * (z0 / (1.f + expf(-z0)));
;       const float g1 = o[i][1] * r * ww.y * (z1 / (1.f + expf(-z1)));
;       const float g2 = o[i][2] * r * ww.z * (z2 / (1.f + expf(-z2)));
;       const float g3 = o[i][3] * r * ww.w * (z3 / (1.f + expf(-z3)));
;       u32x2 ov = {pack2(g0, g1), pack2(g2, g3)};
;       hp[i * 64 + lane] = ov;
	v_add_f32_e32 v172, v172, v180
	v_add_f32_e32 v173, v173, v181
	v_add_f32_e32 v174, v174, v182
	v_add_f32_e32 v175, v175, v183
	v_add_f32_e32 v176, v176, v184
	v_add_f32_e32 v177, v177, v185
	v_add_f32_e32 v178, v178, v186
	v_add_f32_e32 v179, v179, v187
	ds_bpermute_b32 v180, v38, v172
	ds_bpermute_b32 v181, v38, v173
	ds_bpermute_b32 v182, v38, v174
	ds_bpermute_b32 v183, v38, v175
	ds_bpermute_b32 v184, v38, v176
	ds_bpermute_b32 v185, v38, v177
	ds_bpermute_b32 v186, v38, v178
	ds_bpermute_b32 v187, v38, v179
	s_waitcnt lgkmcnt(0)
	v_add_f32_e32 v172, v172, v180
	v_add_f32_e32 v173, v173, v181
	v_add_f32_e32 v174, v174, v182
	v_add_f32_e32 v175, v175, v183
	v_add_f32_e32 v176, v176, v184
	v_add_f32_e32 v177, v177, v185
	v_add_f32_e32 v178, v178, v186
	v_add_f32_e32 v179, v179, v187
	ds_bpermute_b32 v180, v39, v172
	ds_bpermute_b32 v181, v39, v173
	ds_bpermute_b32 v182, v39, v174
	ds_bpermute_b32 v183, v39, v175
	ds_bpermute_b32 v184, v39, v176
	ds_bpermute_b32 v185, v39, v177
	ds_bpermute_b32 v186, v39, v178
	ds_bpermute_b32 v187, v39, v179
	s_waitcnt lgkmcnt(0)
	v_add_f32_e32 v172, v172, v180
	v_add_f32_e32 v173, v173, v181
	v_add_f32_e32 v174, v174, v182
	v_add_f32_e32 v175, v175, v183
	v_add_f32_e32 v176, v176, v184
	v_add_f32_e32 v177, v177, v185
	v_add_f32_e32 v178, v178, v186
	v_add_f32_e32 v179, v179, v187
	v_add_f32_e32 v180, v172, v173
	v_add_f32_e32 v182, v174, v175
	v_add_f32_e32 v184, v176, v177
	v_add_f32_e32 v186, v178, v179
	v_fma_f32 v180, v180, s14, v12
	v_fma_f32 v182, v182, s14, v12
	v_fma_f32 v184, v184, s14, v12
	v_fma_f32 v186, v186, s14, v12
	v_rsq_f32_e32 v180, v180
	v_rsq_f32_e32 v182, v182
	v_rsq_f32_e32 v184, v184
	v_rsq_f32_e32 v186, v186
	s_waitcnt vmcnt(0)
	v_lshlrev_b32_e32 v188, 16, v116
	v_and_b32_e32 v189, 0xffff0000, v116
	v_lshlrev_b32_e32 v190, 16, v117
	v_and_b32_e32 v191, 0xffff0000, v117
	v_mul_f32_e32 v192, 0xbfb8aa3b, v188
	v_mul_f32_e32 v193, 0xbfb8aa3b, v189
	v_mul_f32_e32 v194, 0xbfb8aa3b, v190
	v_mul_f32_e32 v195, 0xbfb8aa3b, v191
	v_exp_f32_e32 v192, v192
	v_exp_f32_e32 v193, v193
	v_exp_f32_e32 v194, v194
	v_exp_f32_e32 v195, v195
	v_mul_f32_e32 v140, v140, v180
	v_mul_f32_e32 v141, v141, v180
	v_mul_f32_e32 v142, v142, v180
	v_mul_f32_e32 v143, v143, v180
	v_add_f32_e32 v192, 1.0, v192
	v_add_f32_e32 v193, 1.0, v193
	v_add_f32_e32 v194, 1.0, v194
	v_add_f32_e32 v195, 1.0, v195
	v_rcp_f32_e32 v192, v192
	v_rcp_f32_e32 v193, v193
	v_rcp_f32_e32 v194, v194
	v_rcp_f32_e32 v195, v195
	v_mul_f32_e32 v140, v140, v132
	v_mul_f32_e32 v141, v141, v133
	v_mul_f32_e32 v142, v142, v134
	v_mul_f32_e32 v143, v143, v135
	v_mul_f32_e32 v192, v188, v192
	v_mul_f32_e32 v193, v189, v193
	v_mul_f32_e32 v194, v190, v194
	v_mul_f32_e32 v195, v191, v195
	v_mul_f32_e32 v140, v140, v192
	v_mul_f32_e32 v141, v141, v193
	v_mul_f32_e32 v142, v142, v194
	v_mul_f32_e32 v143, v143, v195
	v_cvt_pk_bf16_f32 v212, v140, v141
	v_cvt_pk_bf16_f32 v213, v142, v143
	global_store_dwordx2 v[14:15], v[212:213], off
	v_lshlrev_b32_e32 v188, 16, v118
	v_and_b32_e32 v189, 0xffff0000, v118
	v_lshlrev_b32_e32 v190, 16, v119
	v_and_b32_e32 v191, 0xffff0000, v119
	v_mul_f32_e32 v192, 0xbfb8aa3b, v188
	v_mul_f32_e32 v193, 0xbfb8aa3b, v189
	v_mul_f32_e32 v194, 0xbfb8aa3b, v190
	v_mul_f32_e32 v195, 0xbfb8aa3b, v191
	v_exp_f32_e32 v192, v192
	v_exp_f32_e32 v193, v193
	v_exp_f32_e32 v194, v194
	v_exp_f32_e32 v195, v195
	v_mul_f32_e32 v144, v144, v180
	v_mul_f32_e32 v145, v145, v180
	v_mul_f32_e32 v146, v146, v180
	v_mul_f32_e32 v147, v147, v180
	v_add_f32_e32 v192, 1.0, v192
	v_add_f32_e32 v193, 1.0, v193
	v_add_f32_e32 v194, 1.0, v194
	v_add_f32_e32 v195, 1.0, v195
	v_rcp_f32_e32 v192, v192
	v_rcp_f32_e32 v193, v193
	v_rcp_f32_e32 v194, v194
	v_rcp_f32_e32 v195, v195
	v_mul_f32_e32 v144, v144, v136
	v_mul_f32_e32 v145, v145, v137
	v_mul_f32_e32 v146, v146, v138
	v_mul_f32_e32 v147, v147, v139
	v_mul_f32_e32 v192, v188, v192
	v_mul_f32_e32 v193, v189, v193
	v_mul_f32_e32 v194, v190, v194
	v_mul_f32_e32 v195, v191, v195
	v_mul_f32_e32 v144, v144, v192
	v_mul_f32_e32 v145, v145, v193
	v_mul_f32_e32 v146, v146, v194
	v_mul_f32_e32 v147, v147, v195
	v_cvt_pk_bf16_f32 v214, v144, v145
	v_cvt_pk_bf16_f32 v215, v146, v147
	global_store_dwordx2 v[14:15], v[214:215], off offset:512
	v_lshlrev_b32_e32 v188, 16, v120
	v_and_b32_e32 v189, 0xffff0000, v120
	v_lshlrev_b32_e32 v190, 16, v121
	v_and_b32_e32 v191, 0xffff0000, v121
	v_mul_f32_e32 v192, 0xbfb8aa3b, v188
	v_mul_f32_e32 v193, 0xbfb8aa3b, v189
	v_mul_f32_e32 v194, 0xbfb8aa3b, v190
	v_mul_f32_e32 v195, 0xbfb8aa3b, v191
	v_exp_f32_e32 v192, v192
	v_exp_f32_e32 v193, v193
	v_exp_f32_e32 v194, v194
	v_exp_f32_e32 v195, v195
	v_mul_f32_e32 v148, v148, v182
	v_mul_f32_e32 v149, v149, v182
	v_mul_f32_e32 v150, v150, v182
	v_mul_f32_e32 v151, v151, v182
	v_add_f32_e32 v192, 1.0, v192
	v_add_f32_e32 v193, 1.0, v193
	v_add_f32_e32 v194, 1.0, v194
	v_add_f32_e32 v195, 1.0, v195
	v_rcp_f32_e32 v192, v192
	v_rcp_f32_e32 v193, v193
	v_rcp_f32_e32 v194, v194
	v_rcp_f32_e32 v195, v195
	v_mul_f32_e32 v148, v148, v132
	v_mul_f32_e32 v149, v149, v133
	v_mul_f32_e32 v150, v150, v134
	v_mul_f32_e32 v151, v151, v135
	v_mul_f32_e32 v192, v188, v192
	v_mul_f32_e32 v193, v189, v193
	v_mul_f32_e32 v194, v190, v194
	v_mul_f32_e32 v195, v191, v195
	v_mul_f32_e32 v148, v148, v192
	v_mul_f32_e32 v149, v149, v193
	v_mul_f32_e32 v150, v150, v194
	v_mul_f32_e32 v151, v151, v195
	v_cvt_pk_bf16_f32 v216, v148, v149
	v_cvt_pk_bf16_f32 v217, v150, v151
	global_store_dwordx2 v[14:15], v[216:217], off offset:1024
	v_lshlrev_b32_e32 v188, 16, v122
	v_and_b32_e32 v189, 0xffff0000, v122
	v_lshlrev_b32_e32 v190, 16, v123
; DI u32 pack2(float a, float b) { f32v2 v = {a, b}; return __builtin_bit_cast(u32, __builtin_convertvector(v, bf16v2)); }
; DI float bflo(u32 p) { return __uint_as_float(p << 16); }
; DI float bfhi(u32 p) { return __uint_as_float(p & 0xffff0000u); }
; DI void gate_phase(u16* hb, const u16* proj, int ld, int zoff, const float* w, int G, float scale) {
;     ...
; #pragma unroll
;     for (int i = 0; i < 8; ++i) {
;       const float r = rsqrtf(ss[i] * invG + 1e-6f) * scale;
;       const int col = i * 256 + lane * 4;
;       const float4 ww = *reinterpret_cast<const float4*>(w + (col & (G - 1)));
;       const u32x2 zk = __builtin_nontemporal_load(zp + i * 64 + lane);
;       const float z0 = bflo(zk.x), z1 = bfhi(zk.x), z2 = bflo(zk.y), z3 = bfhi(zk.y);
;       const float g0 = o[i][0] * r * ww.x * (z0 / (1.f + expf(-z0)));
;       const float g1 = o[i][1] * r * ww.y * (z1 / (1.f + expf(-z1)));
;       const float g2 = o[i][2] * r * ww.z * (z2 / (1.f + expf(-z2)));
;       const float g3 = o[i][3] * r * ww.w * (z3 / (1.f + expf(-z3)));
;       u32x2 ov = {pack2(g0, g1), pack2(g2, g3)};
;       hp[i * 64 + lane] = ov;
;     }
	v_and_b32_e32 v191, 0xffff0000, v123
	v_mul_f32_e32 v192, 0xbfb8aa3b, v188
	v_mul_f32_e32 v193, 0xbfb8aa3b, v189
	v_mul_f32_e32 v194, 0xbfb8aa3b, v190
	v_mul_f32_e32 v195, 0xbfb8aa3b, v191
	v_exp_f32_e32 v192, v192
	v_exp_f32_e32 v193, v193
	v_exp_f32_e32 v194, v194
	v_exp_f32_e32 v195, v195
	v_mul_f32_e32 v152, v152, v182
	v_mul_f32_e32 v153, v153, v182
	v_mul_f32_e32 v154, v154, v182
	v_mul_f32_e32 v155, v155, v182
	v_add_f32_e32 v192, 1.0, v192
	v_add_f32_e32 v193, 1.0, v193
	v_add_f32_e32 v194, 1.0, v194
	v_add_f32_e32 v195, 1.0, v195
	v_rcp_f32_e32 v192, v192
	v_rcp_f32_e32 v193, v193
	v_rcp_f32_e32 v194, v194
	v_rcp_f32_e32 v195, v195
	v_mul_f32_e32 v152, v152, v136
	v_mul_f32_e32 v153, v153, v137
	v_mul_f32_e32 v154, v154, v138
	v_mul_f32_e32 v155, v155, v139
	v_mul_f32_e32 v192, v188, v192
	v_mul_f32_e32 v193, v189, v193
	v_mul_f32_e32 v194, v190, v194
	v_mul_f32_e32 v195, v191, v195
	v_mul_f32_e32 v152, v152, v192
	v_mul_f32_e32 v153, v153, v193
	v_mul_f32_e32 v154, v154, v194
	v_mul_f32_e32 v155, v155, v195
	v_cvt_pk_bf16_f32 v218, v152, v153
	v_cvt_pk_bf16_f32 v219, v154, v155
	global_store_dwordx2 v[14:15], v[218:219], off offset:1536
	v_lshlrev_b32_e32 v188, 16, v124
	v_and_b32_e32 v189, 0xffff0000, v124
	v_lshlrev_b32_e32 v190, 16, v125
	v_and_b32_e32 v191, 0xffff0000, v125
	v_mul_f32_e32 v192, 0xbfb8aa3b, v188
	v_mul_f32_e32 v193, 0xbfb8aa3b, v189
	v_mul_f32_e32 v194, 0xbfb8aa3b, v190
	v_mul_f32_e32 v195, 0xbfb8aa3b, v191
	v_exp_f32_e32 v192, v192
	v_exp_f32_e32 v193, v193
	v_exp_f32_e32 v194, v194
	v_exp_f32_e32 v195, v195
	v_mul_f32_e32 v156, v156, v184
	v_mul_f32_e32 v157, v157, v184
	v_mul_f32_e32 v158, v158, v184
	v_mul_f32_e32 v159, v159, v184
	v_add_f32_e32 v192, 1.0, v192
	v_add_f32_e32 v193, 1.0, v193
	v_add_f32_e32 v194, 1.0, v194
	v_add_f32_e32 v195, 1.0, v195
	v_rcp_f32_e32 v192, v192
	v_rcp_f32_e32 v193, v193
	v_rcp_f32_e32 v194, v194
	v_rcp_f32_e32 v195, v195
	v_mul_f32_e32 v156, v156, v132
	v_mul_f32_e32 v157, v157, v133
	v_mul_f32_e32 v158, v158, v134
	v_mul_f32_e32 v159, v159, v135
	v_mul_f32_e32 v192, v188, v192
	v_mul_f32_e32 v193, v189, v193
	v_mul_f32_e32 v194, v190, v194
	v_mul_f32_e32 v195, v191, v195
	v_mul_f32_e32 v156, v156, v192
	v_mul_f32_e32 v157, v157, v193
	v_mul_f32_e32 v158, v158, v194
	v_mul_f32_e32 v159, v159, v195
	v_cvt_pk_bf16_f32 v220, v156, v157
	v_cvt_pk_bf16_f32 v221, v158, v159
	global_store_dwordx2 v[14:15], v[220:221], off offset:2048
	v_lshlrev_b32_e32 v188, 16, v126
	v_and_b32_e32 v189, 0xffff0000, v126
	v_lshlrev_b32_e32 v190, 16, v127
	v_and_b32_e32 v191, 0xffff0000, v127
	v_mul_f32_e32 v192, 0xbfb8aa3b, v188
	v_mul_f32_e32 v193, 0xbfb8aa3b, v189
	v_mul_f32_e32 v194, 0xbfb8aa3b, v190
	v_mul_f32_e32 v195, 0xbfb8aa3b, v191
	v_exp_f32_e32 v192, v192
	v_exp_f32_e32 v193, v193
	v_exp_f32_e32 v194, v194
	v_exp_f32_e32 v195, v195
	v_mul_f32_e32 v160, v160, v184
	v_mul_f32_e32 v161, v161, v184
	v_mul_f32_e32 v162, v162, v184
	v_mul_f32_e32 v163, v163, v184
	v_add_f32_e32 v192, 1.0, v192
	v_add_f32_e32 v193, 1.0, v193
	v_add_f32_e32 v194, 1.0, v194
	v_add_f32_e32 v195, 1.0, v195
	v_rcp_f32_e32 v192, v192
	v_rcp_f32_e32 v193, v193
	v_rcp_f32_e32 v194, v194
	v_rcp_f32_e32 v195, v195
	v_mul_f32_e32 v160, v160, v136
	v_mul_f32_e32 v161, v161, v137
	v_mul_f32_e32 v162, v162, v138
	v_mul_f32_e32 v163, v163, v139
	v_mul_f32_e32 v192, v188, v192
	v_mul_f32_e32 v193, v189, v193
	v_mul_f32_e32 v194, v190, v194
	v_mul_f32_e32 v195, v191, v195
	v_mul_f32_e32 v160, v160, v192
	v_mul_f32_e32 v161, v161, v193
	v_mul_f32_e32 v162, v162, v194
	v_mul_f32_e32 v163, v163, v195
	v_cvt_pk_bf16_f32 v222, v160, v161
	v_cvt_pk_bf16_f32 v223, v162, v163
	global_store_dwordx2 v[14:15], v[222:223], off offset:2560
	v_lshlrev_b32_e32 v188, 16, v128
	v_and_b32_e32 v189, 0xffff0000, v128
	v_lshlrev_b32_e32 v190, 16, v129
	v_and_b32_e32 v191, 0xffff0000, v129
	v_mul_f32_e32 v192, 0xbfb8aa3b, v188
	v_mul_f32_e32 v193, 0xbfb8aa3b, v189
	v_mul_f32_e32 v194, 0xbfb8aa3b, v190
	v_mul_f32_e32 v195, 0xbfb8aa3b, v191
	v_exp_f32_e32 v192, v192
	v_exp_f32_e32 v193, v193
	v_exp_f32_e32 v194, v194
	v_exp_f32_e32 v195, v195
	v_mul_f32_e32 v164, v164, v186
	v_mul_f32_e32 v165, v165, v186
	v_mul_f32_e32 v166, v166, v186
	v_mul_f32_e32 v167, v167, v186
	v_add_f32_e32 v192, 1.0, v192
	v_add_f32_e32 v193, 1.0, v193
	v_add_f32_e32 v194, 1.0, v194
	v_add_f32_e32 v195, 1.0, v195
	v_rcp_f32_e32 v192, v192
	v_rcp_f32_e32 v193, v193
	v_rcp_f32_e32 v194, v194
	v_rcp_f32_e32 v195, v195
	v_mul_f32_e32 v164, v164, v132
	v_mul_f32_e32 v165, v165, v133
	v_mul_f32_e32 v166, v166, v134
	v_mul_f32_e32 v167, v167, v135
	v_mul_f32_e32 v192, v188, v192
	v_mul_f32_e32 v193, v189, v193
	v_mul_f32_e32 v194, v190, v194
	v_mul_f32_e32 v195, v191, v195
	v_mul_f32_e32 v164, v164, v192
	v_mul_f32_e32 v165, v165, v193
	v_mul_f32_e32 v166, v166, v194
	v_mul_f32_e32 v167, v167, v195
	v_cvt_pk_bf16_f32 v224, v164, v165
	v_cvt_pk_bf16_f32 v225, v166, v167
	global_store_dwordx2 v[14:15], v[224:225], off offset:3072
	v_lshlrev_b32_e32 v188, 16, v130
	v_and_b32_e32 v189, 0xffff0000, v130
	v_lshlrev_b32_e32 v190, 16, v131
	v_and_b32_e32 v191, 0xffff0000, v131
	v_mul_f32_e32 v192, 0xbfb8aa3b, v188
	v_mul_f32_e32 v193, 0xbfb8aa3b, v189
	v_mul_f32_e32 v194, 0xbfb8aa3b, v190
	v_mul_f32_e32 v195, 0xbfb8aa3b, v191
	v_exp_f32_e32 v192, v192
	v_exp_f32_e32 v193, v193
	v_exp_f32_e32 v194, v194
	v_exp_f32_e32 v195, v195
	v_mul_f32_e32 v168, v168, v186
	v_mul_f32_e32 v169, v169, v186
	v_mul_f32_e32 v170, v170, v186
	v_mul_f32_e32 v171, v171, v186
	v_add_f32_e32 v192, 1.0, v192
	v_add_f32_e32 v193, 1.0, v193
	v_add_f32_e32 v194, 1.0, v194
	v_add_f32_e32 v195, 1.0, v195
	v_rcp_f32_e32 v192, v192
	v_rcp_f32_e32 v193, v193
	v_rcp_f32_e32 v194, v194
	v_rcp_f32_e32 v195, v195
	v_mul_f32_e32 v168, v168, v136
	v_mul_f32_e32 v169, v169, v137
	v_mul_f32_e32 v170, v170, v138
	v_mul_f32_e32 v171, v171, v139
	v_mul_f32_e32 v192, v188, v192
	v_mul_f32_e32 v193, v189, v193
	v_mul_f32_e32 v194, v190, v194
	v_mul_f32_e32 v195, v191, v195
	v_mul_f32_e32 v168, v168, v192
	v_mul_f32_e32 v169, v169, v193
	v_mul_f32_e32 v170, v170, v194
	v_mul_f32_e32 v171, v171, v195
	v_cvt_pk_bf16_f32 v226, v168, v169
	v_cvt_pk_bf16_f32 v227, v170, v171
	global_store_dwordx2 v[14:15], v[226:227], off offset:3584
	v_cmp_lt_i32_e32 vcc, s19, v4
	s_nop 1
	s_or_b64 s[12:13], vcc, s[12:13]
	s_andn2_b64 exec, exec, s[12:13]
	s_cbranch_execnz .LBB0_1483
